# attention phase B: drop the wait between a wave's own K/V tile writes and its reads (per-wave tiles, LDS ops of one wave execute in order)
# speedup vs baseline: 1.0043x; 1.0043x over previous
.LBB0_546:
	s_cmp_eq_u32 s77, 1
	s_cselect_b32 s0, 2, 4
	s_lshr_b32 s1, 16, s0
	s_lshl_b32 s18, s67, 6
	s_waitcnt vmcnt(14) lgkmcnt(2)
	ds_write_b128 v219, v[12:15]
	s_waitcnt vmcnt(12)
	ds_write_b128 v219, v[24:27] offset:1152
	s_waitcnt vmcnt(10)
	ds_write_b128 v219, v[32:35] offset:2304
	s_waitcnt vmcnt(8)
	ds_write_b128 v219, v[40:43] offset:3456
	s_waitcnt vmcnt(6)
	ds_write_b128 v219, v[52:55] offset:4608
	s_waitcnt vmcnt(4)
	ds_write_b128 v219, v[64:67] offset:5760
	s_waitcnt vmcnt(2)
	ds_write_b128 v219, v[76:79] offset:6912
	s_waitcnt vmcnt(0)
	ds_write_b128 v219, v[88:91] offset:8064
	s_waitcnt lgkmcnt(8)
	ds_write_b128 v220, v[4:7] offset:9216
	ds_write_b128 v220, v[8:11] offset:10240
	ds_write_b128 v220, v[16:19] offset:11264
	ds_write_b128 v220, v[20:23] offset:12288
	ds_write_b128 v220, v[28:31] offset:13312
	ds_write_b128 v220, v[36:39] offset:14336
	ds_write_b128 v220, v[44:47] offset:15360
	ds_write_b128 v220, v[68:71] offset:16384
	v_mul_u32_u24_e32 v2, s1, v173
	s_sub_i32 s16, 0x80, s18
	s_lshr_b32 s0, s8, s0
	v_mov_b32_e32 v3, s16
	s_sub_i32 s19, s16, s0
	v_subrev_u32_e32 v2, s18, v2
	v_add_u32_e32 v228, v207, v192
	v_add_u32_e32 v230, v207, v194
	v_mad_u32_u24 v18, s1, v173, v3
	s_cmp_lg_u32 s77, 2
	v_max_i32_e32 v19, s19, v2
	v_add_u32_e32 v229, v207, v193
	ds_read_b128 v[10:13], v228 offset:9216
	ds_read_b128 v[14:17], v229 offset:9216
	v_add_u32_e32 v231, v207, v195
	ds_read_b128 v[6:9], v230 offset:9728
	ds_read_b128 v[2:5], v231 offset:9728
	s_cselect_b64 s[0:1], -1, 0
	s_cmp_lg_u32 s67, 2
	s_cselect_b64 s[16:17], -1, 0
	s_or_b64 s[0:1], s[16:17], s[0:1]
	v_sub_u32_e32 v18, v18, v19
	v_sub_u32_e32 v25, v176, v19
	s_mov_b64 s[16:17], -1
	s_and_b64 vcc, exec, s[0:1]
	v_add_u32_e32 v225, s45, v175
	v_cmp_le_u32_e64 s[0:1], v25, v18
	v_add_u32_e32 v26, 1, v25
	v_add_u32_e32 v24, 2, v25
	v_add_u32_e32 v23, 3, v25
	v_add_u32_e32 v22, 4, v25
	v_add_u32_e32 v21, 5, v25
	v_add_u32_e32 v20, 6, v25
	v_add_u32_e32 v19, 7, v25
	s_cbranch_vccz .LBB0_548
	s_waitcnt vmcnt(1) lgkmcnt(3)
	v_mfma_f32_16x16x32_bf16 v[28:31], v[10:13], v[132:135], 0
	ds_read_b128 v[32:35], v228 offset:13312
	ds_read_b128 v[36:39], v229 offset:13312
	v_cmp_le_u32_e32 vcc, v26, v18
	ds_read_b128 v[40:43], v230 offset:13824
	ds_read_b128 v[44:47], v231 offset:13824
	s_waitcnt vmcnt(0) lgkmcnt(6)
	v_mfma_f32_16x16x32_bf16 v[28:31], v[14:17], v[136:139], v[28:31]
	s_mov_b64 s[16:17], 0
	s_waitcnt lgkmcnt(5)
	v_mfma_f32_16x16x32_bf16 v[52:55], v[6:9], v[132:135], 0
	s_waitcnt lgkmcnt(4)
	v_mfma_f32_16x16x32_bf16 v[52:55], v[2:5], v[136:139], v[52:55]
	s_nop 2
	v_cndmask_b32_e32 v64, v217, v29, vcc
	v_cmp_le_u32_e32 vcc, v24, v18
	v_cndmask_b32_e64 v27, v217, v28, s[0:1]
	s_nop 0
	v_cndmask_b32_e32 v65, v217, v30, vcc
	v_cmp_le_u32_e32 vcc, v23, v18
	s_nop 1
	v_cndmask_b32_e32 v66, v217, v31, vcc
	s_waitcnt lgkmcnt(3)
	v_mfma_f32_16x16x32_bf16 v[28:31], v[32:35], v[132:135], 0
	v_cmp_le_u32_e32 vcc, v22, v18
	s_nop 1
	v_cndmask_b32_e32 v52, v217, v52, vcc
	v_cmp_le_u32_e32 vcc, v21, v18
	s_waitcnt lgkmcnt(2)
	v_mfma_f32_16x16x32_bf16 v[28:31], v[36:39], v[136:139], v[28:31]
	v_add_u32_e32 v37, 32, v25
	v_cndmask_b32_e32 v53, v217, v53, vcc
	v_cmp_le_u32_e32 vcc, v20, v18
	s_waitcnt lgkmcnt(1)
	v_mfma_f32_16x16x32_bf16 v[32:35], v[40:43], v[132:135], 0
	v_cndmask_b32_e32 v54, v217, v54, vcc
	v_cmp_le_u32_e32 vcc, v19, v18
	s_waitcnt lgkmcnt(0)
	v_mfma_f32_16x16x32_bf16 v[32:35], v[44:47], v[136:139], v[32:35]
	v_cndmask_b32_e32 v36, v217, v55, vcc
	v_cmp_le_u32_e32 vcc, v37, v18
	v_add_u32_e32 v37, 33, v25
	s_nop 0
	v_cndmask_b32_e32 v28, v217, v28, vcc
	v_cmp_le_u32_e32 vcc, v37, v18
	v_add_u32_e32 v37, 34, v25
	s_nop 0
	v_cndmask_b32_e32 v29, v217, v29, vcc
	v_cmp_le_u32_e32 vcc, v37, v18
	v_add_u32_e32 v37, 35, v25
	s_nop 0
	v_cndmask_b32_e32 v30, v217, v30, vcc
	v_cmp_le_u32_e32 vcc, v37, v18
	v_add_u32_e32 v37, 36, v25
	s_nop 0
	v_cndmask_b32_e32 v31, v217, v31, vcc
	v_cmp_le_u32_e32 vcc, v37, v18
	v_add_u32_e32 v37, 37, v25
	s_nop 0
	v_cndmask_b32_e32 v32, v217, v32, vcc
	v_cmp_le_u32_e32 vcc, v37, v18
	v_add_u32_e32 v37, 38, v25
	s_nop 0
	v_cndmask_b32_e32 v33, v217, v33, vcc
	v_cmp_le_u32_e32 vcc, v37, v18
	v_add_u32_e32 v37, 39, v25
	s_nop 0
	v_cndmask_b32_e32 v34, v217, v34, vcc
	v_cmp_le_u32_e32 vcc, v37, v18
	v_max3_f32 v37, v27, s62, v64
	v_max3_f32 v37, v37, v65, v66
	v_max3_f32 v37, v37, v52, v53
	v_max3_f32 v37, v37, v54, v36
	v_max3_f32 v37, v37, v28, v29
	v_max3_f32 v37, v37, v30, v31
	v_cndmask_b32_e32 v35, v217, v35, vcc
	v_max3_f32 v37, v37, v32, v33
	v_max3_f32 v37, v37, v34, v35
	ds_bpermute_b32 v38, v0, v37
	s_waitcnt lgkmcnt(0)
	v_max_f32_e32 v38, v38, v38
	v_max_f32_e32 v37, v37, v38
	ds_bpermute_b32 v38, v222, v37
	s_waitcnt lgkmcnt(0)
	v_max3_f32 v226, v223, v37, v38
	v_sub_f32_e32 v27, v27, v226
	v_exp_f32_e32 v27, v27
	v_sub_f32_e32 v38, v64, v226
	v_exp_f32_e32 v38, v38
	v_sub_f32_e32 v39, v65, v226
	v_sub_f32_e32 v28, v28, v226
	v_exp_f32_e32 v39, v39
	v_sub_f32_e32 v40, v66, v226
	v_exp_f32_e32 v90, v28
	v_sub_f32_e32 v28, v29, v226
	v_exp_f32_e32 v40, v40
	v_sub_f32_e32 v42, v52, v226
	v_exp_f32_e32 v91, v28
	v_sub_f32_e32 v28, v30, v226
	v_add_f32_e32 v41, 0, v27
	v_exp_f32_e32 v42, v42
	v_sub_f32_e32 v43, v53, v226
	v_exp_f32_e32 v156, v28
	v_sub_f32_e32 v28, v31, v226
	v_add_f32_e32 v41, v38, v41
	v_exp_f32_e32 v43, v43
	v_sub_f32_e32 v44, v54, v226
	v_exp_f32_e32 v160, v28
	v_sub_f32_e32 v28, v32, v226
	v_add_f32_e32 v41, v39, v41
	v_exp_f32_e32 v44, v44
	v_sub_f32_e32 v36, v36, v226
	v_exp_f32_e32 v161, v28
	v_sub_f32_e32 v28, v33, v226
	v_sub_f32_e32 v37, v223, v226
	v_add_f32_e32 v41, v40, v41
	v_exp_f32_e32 v36, v36
	v_exp_f32_e32 v162, v28
	v_sub_f32_e32 v28, v34, v226
	v_add_f32_e32 v41, v42, v41
	v_exp_f32_e32 v164, v28
	v_sub_f32_e32 v64, v35, v226
	v_exp_f32_e32 v88, v37
	v_cvt_pk_bf16_f32 v28, v27, v38
	v_cvt_pk_bf16_f32 v29, v39, v40
	v_cvt_pk_bf16_f32 v30, v42, v43
	v_cvt_pk_bf16_f32 v31, v44, v36
	ds_read_b64_tr_b16 v[34:35], v225 offset:576
	ds_read_b64_tr_b16 v[32:33], v225
	v_add_f32_e32 v41, v43, v41
	v_add_f32_e32 v41, v44, v41
	v_add_f32_e32 v89, v36, v41
	ds_read_b64_tr_b16 v[42:43], v225 offset:608
	ds_read_b64_tr_b16 v[40:41], v225 offset:32
	ds_read_b64_tr_b16 v[44:45], v225 offset:64
	ds_read_b64_tr_b16 v[52:53], v225 offset:96
	ds_read_b64_tr_b16 v[46:47], v225 offset:640
	ds_read_b64_tr_b16 v[54:55], v225 offset:672
	v_pk_mul_f32 v[38:39], v[154:155], v[88:89] op_sel_hi:[1,0]
	v_pk_mul_f32 v[36:37], v[152:153], v[88:89] op_sel_hi:[1,0]
	v_exp_f32_e32 v27, v64
	v_pk_mul_f32 v[66:67], v[142:143], v[88:89] op_sel_hi:[1,0]
	s_waitcnt lgkmcnt(6)
	v_mfma_f32_16x16x32_bf16 v[32:35], v[32:35], v[28:31], v[36:39]
	v_mul_f32_e64 v64, v140, v88
	v_mul_f32_e64 v65, v141, v88
	s_nop 0
	v_pk_mul_f32 v[38:39], v[150:151], v[88:89] op_sel_hi:[1,0]
	v_pk_mul_f32 v[36:37], v[148:149], v[88:89] op_sel_hi:[1,0]
	s_waitcnt lgkmcnt(4)
	s_nop 0
	v_mfma_f32_16x16x32_bf16 v[36:39], v[40:43], v[28:31], v[36:39]
	v_mul_f32_e64 v42, v146, v88
	v_mul_f32_e64 v43, v147, v88
	v_pk_mul_f32 v[40:41], v[144:145], v[88:89] op_sel_hi:[1,0]
	s_waitcnt lgkmcnt(1)
	s_nop 0
	v_mfma_f32_16x16x32_bf16 v[40:43], v[44:47], v[28:31], v[40:43]
	v_cvt_pk_bf16_f32 v44, v90, v91
	v_cvt_pk_bf16_f32 v45, v156, v160
	v_cvt_pk_bf16_f32 v46, v161, v162
	v_cvt_pk_bf16_f32 v47, v164, v27
	ds_read_b64_tr_b16 v[70:71], v225 offset:5184
	ds_read_b64_tr_b16 v[68:69], v225 offset:4608
	s_waitcnt lgkmcnt(0)
	v_mfma_f32_16x16x32_bf16 v[168:171], v[68:71], v[44:47], v[32:35]
	s_nop 2
	v_add_f32_e32 v32, v90, v89
	v_add_f32_e32 v32, v91, v32
	v_add_f32_e32 v32, v156, v32
	v_mfma_f32_16x16x32_bf16 v[28:31], v[52:55], v[28:31], v[64:67]
	ds_read_b64_tr_b16 v[54:55], v225 offset:5216
	ds_read_b64_tr_b16 v[52:53], v225 offset:4640
	s_nop 0
	ds_read_b64_tr_b16 v[64:65], v225 offset:4672
	ds_read_b64_tr_b16 v[76:77], v225 offset:4704
	ds_read_b64_tr_b16 v[66:67], v225 offset:5248
	ds_read_b64_tr_b16 v[78:79], v225 offset:5280
	v_add_f32_e32 v32, v160, v32
	v_add_f32_e32 v32, v161, v32
	v_add_f32_e32 v32, v162, v32
	s_waitcnt lgkmcnt(0)
	v_add_f32_e32 v32, v164, v32
	v_add_f32_e32 v227, v27, v32
	s_waitcnt lgkmcnt(4)
	v_mfma_f32_16x16x32_bf16 v[156:159], v[52:55], v[44:47], v[36:39]
	v_fmac_f32_e32 v227, v224, v88
	s_waitcnt lgkmcnt(1)
	v_mfma_f32_16x16x32_bf16 v[160:163], v[64:67], v[44:47], v[40:43]
	s_waitcnt lgkmcnt(0)
	v_mfma_f32_16x16x32_bf16 v[164:167], v[76:79], v[44:47], v[28:31]

.LBB0_555:
	s_add_i32 s67, s67, 1
	s_and_b64 s[0:1], s[38:39], exec
	s_cselect_b32 s14, s66, s67
	s_and_b64 s[0:1], s[18:19], exec
	s_cselect_b32 s78, s67, s14
	s_xor_b64 s[0:1], s[18:19], -1
	v_cndmask_b32_e64 v2, 0, 1, s[0:1]
	s_waitcnt vmcnt(32)
	ds_write_b128 v219, v[48:51]
	s_waitcnt vmcnt(30)
	ds_write_b128 v219, v[60:63] offset:1152
	s_waitcnt vmcnt(28)
	ds_write_b128 v219, v[80:83] offset:2304
	s_waitcnt vmcnt(26)
	ds_write_b128 v219, v[92:95] offset:3456
	s_waitcnt vmcnt(24)
	ds_write_b128 v219, v[100:103] offset:4608
	s_waitcnt vmcnt(22)
	ds_write_b128 v219, v[108:111] offset:5760
	s_waitcnt vmcnt(20)
	ds_write_b128 v219, v[116:119] offset:6912
	s_waitcnt vmcnt(18)
	ds_write_b128 v219, v[124:127] offset:8064
	ds_write_b128 v220, v[56:59] offset:9216
	ds_write_b128 v220, v[72:75] offset:10240
	ds_write_b128 v220, v[84:87] offset:11264
	ds_write_b128 v220, v[96:99] offset:12288
	ds_write_b128 v220, v[104:107] offset:13312
	ds_write_b128 v220, v[112:115] offset:14336
	ds_write_b128 v220, v[120:123] offset:15360
	ds_write_b128 v220, v[128:131] offset:16384
	v_readfirstlane_b32 s0, v2
	s_add_i32 s67, s77, s0
	s_cmp_eq_u32 s67, 1
	s_cselect_b32 s0, 2, 4
	s_lshl_b32 s20, s78, 6
	s_lshr_b32 s1, 16, s0
	s_sub_i32 s18, 0x80, s20
	s_lshr_b32 s0, s8, s0
	ds_read_b128 v[60:63], v228 offset:9216
	ds_read_b128 v[72:75], v229 offset:9216
	ds_read_b128 v[56:59], v230 offset:9728
	ds_read_b128 v[48:51], v231 offset:9728
	s_sub_i32 s21, s18, s0
	v_mul_u32_u24_e32 v2, s1, v173
	v_mov_b32_e32 v3, s18
	s_cmp_lg_u32 s67, 2
	v_mad_u32_u24 v3, s1, v173, v3
	s_cselect_b64 s[0:1], -1, 0
	s_cmp_lg_u32 s78, 2
	v_subrev_u32_e32 v2, s20, v2
	s_cselect_b64 s[18:19], -1, 0
	v_max_i32_e32 v80, s21, v2
	s_or_b64 s[0:1], s[0:1], s[18:19]
	v_sub_u32_e32 v2, v3, v80
	v_sub_u32_e32 v85, v176, v80
	s_mov_b64 s[14:15], -1
	s_and_b64 vcc, exec, s[0:1]
	v_cmp_le_u32_e64 s[0:1], v85, v2
	v_add_u32_e32 v86, 1, v85
	v_add_u32_e32 v84, 2, v85
	v_add_u32_e32 v83, 3, v85
	v_add_u32_e32 v82, 4, v85
	v_add_u32_e32 v81, 5, v85
	v_add_u32_e32 v80, 6, v85
	v_add_u32_e32 v3, 7, v85
	s_cbranch_vccz .LBB0_557
	s_waitcnt vmcnt(17) lgkmcnt(3)
	v_mfma_f32_16x16x32_bf16 v[92:95], v[60:63], v[132:135], 0
	ds_read_b128 v[96:99], v228 offset:13312
	ds_read_b128 v[100:103], v229 offset:13312
	v_cmp_le_u32_e32 vcc, v86, v2
	ds_read_b128 v[104:107], v230 offset:13824
	ds_read_b128 v[108:111], v231 offset:13824
	s_waitcnt vmcnt(16) lgkmcnt(6)
	v_mfma_f32_16x16x32_bf16 v[92:95], v[72:75], v[136:139], v[92:95]
	s_mov_b64 s[14:15], 0
	s_waitcnt lgkmcnt(5)
	v_mfma_f32_16x16x32_bf16 v[112:115], v[56:59], v[132:135], 0
	s_waitcnt lgkmcnt(4)
	v_mfma_f32_16x16x32_bf16 v[112:115], v[48:51], v[136:139], v[112:115]
	s_nop 2
	v_cndmask_b32_e32 v116, v217, v93, vcc
	v_cmp_le_u32_e32 vcc, v84, v2
	v_cndmask_b32_e64 v87, v217, v92, s[0:1]
	s_nop 0
	v_cndmask_b32_e32 v117, v217, v94, vcc
	v_cmp_le_u32_e32 vcc, v83, v2
	s_nop 1
	v_cndmask_b32_e32 v118, v217, v95, vcc
	s_waitcnt lgkmcnt(3)
	v_mfma_f32_16x16x32_bf16 v[92:95], v[96:99], v[132:135], 0
	v_cmp_le_u32_e32 vcc, v82, v2
	s_nop 1
	v_cndmask_b32_e32 v112, v217, v112, vcc
	v_cmp_le_u32_e32 vcc, v81, v2
	s_waitcnt lgkmcnt(2)
	v_mfma_f32_16x16x32_bf16 v[92:95], v[100:103], v[136:139], v[92:95]
	v_add_u32_e32 v101, 32, v85
	v_cndmask_b32_e32 v113, v217, v113, vcc
	v_cmp_le_u32_e32 vcc, v80, v2
	s_waitcnt lgkmcnt(1)
	v_mfma_f32_16x16x32_bf16 v[96:99], v[104:107], v[132:135], 0
	v_cndmask_b32_e32 v114, v217, v114, vcc
	v_cmp_le_u32_e32 vcc, v3, v2
	s_waitcnt lgkmcnt(0)
	v_mfma_f32_16x16x32_bf16 v[96:99], v[108:111], v[136:139], v[96:99]
	v_cndmask_b32_e32 v100, v217, v115, vcc
	v_cmp_le_u32_e32 vcc, v101, v2
	v_add_u32_e32 v101, 33, v85
	s_nop 0
	v_cndmask_b32_e32 v92, v217, v92, vcc
	v_cmp_le_u32_e32 vcc, v101, v2
	v_add_u32_e32 v101, 34, v85
	s_nop 0
	v_cndmask_b32_e32 v93, v217, v93, vcc
	v_cmp_le_u32_e32 vcc, v101, v2
	v_add_u32_e32 v101, 35, v85
	s_nop 0
	v_cndmask_b32_e32 v94, v217, v94, vcc
	v_cmp_le_u32_e32 vcc, v101, v2
	v_add_u32_e32 v101, 36, v85
	s_nop 0
	v_cndmask_b32_e32 v95, v217, v95, vcc
	v_cmp_le_u32_e32 vcc, v101, v2
	v_add_u32_e32 v101, 37, v85
	s_nop 0
	v_cndmask_b32_e32 v96, v217, v96, vcc
	v_cmp_le_u32_e32 vcc, v101, v2
	v_add_u32_e32 v101, 38, v85
	s_nop 0
	v_cndmask_b32_e32 v97, v217, v97, vcc
	v_cmp_le_u32_e32 vcc, v101, v2
	v_add_u32_e32 v101, 39, v85
	s_nop 0
	v_cndmask_b32_e32 v98, v217, v98, vcc
	v_cmp_le_u32_e32 vcc, v101, v2
	v_max3_f32 v101, v87, s62, v116
	v_max3_f32 v101, v101, v117, v118
	v_max3_f32 v101, v101, v112, v113
	v_max3_f32 v101, v101, v114, v100
	v_max3_f32 v101, v101, v92, v93
	v_max3_f32 v101, v101, v94, v95
	v_cndmask_b32_e32 v99, v217, v99, vcc
	v_max3_f32 v101, v101, v96, v97
	v_max3_f32 v101, v101, v98, v99
	ds_bpermute_b32 v102, v0, v101
	s_waitcnt lgkmcnt(0)
	v_max_f32_e32 v102, v102, v102
	v_max_f32_e32 v101, v101, v102
	ds_bpermute_b32 v102, v222, v101
	s_waitcnt lgkmcnt(0)
	v_max3_f32 v223, v226, v101, v102
	v_sub_f32_e32 v87, v87, v223
	v_exp_f32_e32 v87, v87
	v_sub_f32_e32 v102, v116, v223
	v_exp_f32_e32 v102, v102
	v_sub_f32_e32 v103, v117, v223
	v_sub_f32_e32 v92, v92, v223
	v_exp_f32_e32 v103, v103
	v_sub_f32_e32 v104, v118, v223
	v_exp_f32_e32 v130, v92
	v_sub_f32_e32 v92, v93, v223
	v_exp_f32_e32 v104, v104
	v_sub_f32_e32 v106, v112, v223
	v_exp_f32_e32 v131, v92
	v_sub_f32_e32 v92, v94, v223
	v_add_f32_e32 v105, 0, v87
	v_exp_f32_e32 v106, v106
	v_sub_f32_e32 v107, v113, v223
	v_exp_f32_e32 v140, v92
	v_sub_f32_e32 v92, v95, v223
	v_add_f32_e32 v105, v102, v105
	v_exp_f32_e32 v107, v107
	v_sub_f32_e32 v108, v114, v223
	v_exp_f32_e32 v141, v92
	v_sub_f32_e32 v92, v96, v223
	v_add_f32_e32 v105, v103, v105
	v_exp_f32_e32 v108, v108
	v_sub_f32_e32 v100, v100, v223
	v_exp_f32_e32 v142, v92
	v_sub_f32_e32 v92, v97, v223
	v_sub_f32_e32 v101, v226, v223
	v_add_f32_e32 v105, v104, v105
	v_exp_f32_e32 v100, v100
	v_exp_f32_e32 v143, v92
	v_sub_f32_e32 v92, v98, v223
	v_add_f32_e32 v105, v106, v105
	v_exp_f32_e32 v224, v92
	v_sub_f32_e32 v116, v99, v223
	v_exp_f32_e32 v128, v101
	v_cvt_pk_bf16_f32 v92, v87, v102
	v_cvt_pk_bf16_f32 v93, v103, v104
	v_cvt_pk_bf16_f32 v94, v106, v107
	v_cvt_pk_bf16_f32 v95, v108, v100
	ds_read_b64_tr_b16 v[98:99], v225 offset:576
	ds_read_b64_tr_b16 v[96:97], v225
	v_add_f32_e32 v105, v107, v105
	v_add_f32_e32 v105, v108, v105
	v_add_f32_e32 v129, v100, v105
	ds_read_b64_tr_b16 v[106:107], v225 offset:608
	ds_read_b64_tr_b16 v[104:105], v225 offset:32
	ds_read_b64_tr_b16 v[108:109], v225 offset:64
	ds_read_b64_tr_b16 v[112:113], v225 offset:96
	ds_read_b64_tr_b16 v[110:111], v225 offset:640
	ds_read_b64_tr_b16 v[114:115], v225 offset:672
	v_pk_mul_f32 v[102:103], v[170:171], v[128:129] op_sel_hi:[1,0]
	v_pk_mul_f32 v[100:101], v[168:169], v[128:129] op_sel_hi:[1,0]
	v_exp_f32_e32 v87, v116
	v_pk_mul_f32 v[118:119], v[166:167], v[128:129] op_sel_hi:[1,0]
	s_waitcnt lgkmcnt(6)
	v_mfma_f32_16x16x32_bf16 v[96:99], v[96:99], v[92:95], v[100:103]
	v_mul_f32_e64 v116, v164, v128
	v_mul_f32_e64 v117, v165, v128
	s_nop 0
	v_pk_mul_f32 v[102:103], v[158:159], v[128:129] op_sel_hi:[1,0]
	v_pk_mul_f32 v[100:101], v[156:157], v[128:129] op_sel_hi:[1,0]
	s_waitcnt lgkmcnt(4)
	s_nop 0
	v_mfma_f32_16x16x32_bf16 v[100:103], v[104:107], v[92:95], v[100:103]
	v_mul_f32_e64 v106, v162, v128
	v_mul_f32_e64 v107, v163, v128
	v_pk_mul_f32 v[104:105], v[160:161], v[128:129] op_sel_hi:[1,0]
	s_waitcnt lgkmcnt(1)
	s_nop 0
	v_mfma_f32_16x16x32_bf16 v[104:107], v[108:111], v[92:95], v[104:107]
	v_cvt_pk_bf16_f32 v108, v130, v131
	v_cvt_pk_bf16_f32 v109, v140, v141
	v_cvt_pk_bf16_f32 v110, v142, v143
	v_cvt_pk_bf16_f32 v111, v224, v87
	ds_read_b64_tr_b16 v[122:123], v225 offset:5184
	ds_read_b64_tr_b16 v[120:121], v225 offset:4608
	s_waitcnt lgkmcnt(0)
	v_mfma_f32_16x16x32_bf16 v[152:155], v[120:123], v[108:111], v[96:99]
	s_nop 2
	v_add_f32_e32 v96, v130, v129
	v_add_f32_e32 v96, v131, v96
	v_add_f32_e32 v96, v140, v96
	v_mfma_f32_16x16x32_bf16 v[92:95], v[112:115], v[92:95], v[116:119]
	ds_read_b64_tr_b16 v[114:115], v225 offset:5216
	ds_read_b64_tr_b16 v[112:113], v225 offset:4640
	s_nop 0
	ds_read_b64_tr_b16 v[116:117], v225 offset:4672
	ds_read_b64_tr_b16 v[124:125], v225 offset:4704
	ds_read_b64_tr_b16 v[118:119], v225 offset:5248
	ds_read_b64_tr_b16 v[126:127], v225 offset:5280
	v_add_f32_e32 v96, v141, v96
	v_add_f32_e32 v96, v142, v96
	v_add_f32_e32 v96, v143, v96
	s_waitcnt lgkmcnt(0)
	v_add_f32_e32 v96, v224, v96
	v_add_f32_e32 v224, v87, v96
	s_waitcnt lgkmcnt(4)
	v_mfma_f32_16x16x32_bf16 v[148:151], v[112:115], v[108:111], v[100:103]
	v_fmac_f32_e32 v224, v227, v128
	s_waitcnt lgkmcnt(1)
	v_mfma_f32_16x16x32_bf16 v[144:147], v[116:119], v[108:111], v[104:107]
	s_waitcnt lgkmcnt(0)
	v_mfma_f32_16x16x32_bf16 v[140:143], v[124:127], v[108:111], v[92:95]
